# selected-block stream rewritten with 32x32x16 MFMA (bias via MFMA, P kept as accumulator-operand, LDS transposes at exit) + top-k early exit
# speedup vs baseline: 1.0246x; 1.0052x over previous
.LBB0_159:
	s_or_b64 exec, exec, s[8:9]
	s_waitcnt lgkmcnt(0)
	v_add_f32_e32 v3, v3, v20
	v_cmp_ne_u32_e32 vcc, s12, v219
	s_brev_b32 s9, -4
	s_nop 0
	v_cndmask_b32_e32 v3, v196, v3, vcc
	v_cmp_ge_i32_e32 vcc, s12, v219
	s_nop 1
	v_cndmask_b32_e32 v3, 0, v3, vcc
	v_cmp_lt_u32_e32 vcc, s9, v2
	s_bcnt1_i32_b64 s8, vcc
	v_cmp_lt_u32_e32 vcc, s9, v3
	s_bcnt1_i32_b64 s9, vcc
	s_add_i32 s9, s9, s8
	s_cmp_gt_u32 s9, 15
	s_cselect_b32 s8, 2.0, 0
	s_or_b32 s9, s8, 0x20000000
	v_cmp_le_u32_e32 vcc, s9, v2
	s_bcnt1_i32_b64 s12, vcc
	s_cmp_gt_u32 s12, 15
	s_cselect_b32 s8, s9, s8
	s_cmp_eq_u32 s12, 16
	s_cbranch_scc1 .Ltopk_tail1
	s_or_b32 s9, s8, 0x10000000
	v_cmp_le_u32_e32 vcc, s9, v2
	s_bcnt1_i32_b64 s12, vcc
	s_cmp_gt_u32 s12, 15
	s_cselect_b32 s8, s9, s8
	s_cmp_eq_u32 s12, 16
	s_cbranch_scc1 .Ltopk_tail1
	s_or_b32 s9, s8, 0x8000000
	v_cmp_le_u32_e32 vcc, s9, v2
	s_bcnt1_i32_b64 s12, vcc
	s_cmp_gt_u32 s12, 15
	s_cselect_b32 s8, s9, s8
	s_cmp_eq_u32 s12, 16
	s_cbranch_scc1 .Ltopk_tail1
	s_or_b32 s9, s8, 0x4000000
	v_cmp_le_u32_e32 vcc, s9, v2
	s_bcnt1_i32_b64 s12, vcc
	s_cmp_gt_u32 s12, 15
	s_cselect_b32 s8, s9, s8
	s_cmp_eq_u32 s12, 16
	s_cbranch_scc1 .Ltopk_tail1
	s_or_b32 s9, s8, 0x2000000
	v_cmp_le_u32_e32 vcc, s9, v2
	s_bcnt1_i32_b64 s12, vcc
	s_cmp_gt_u32 s12, 15
	s_cselect_b32 s8, s9, s8
	s_cmp_eq_u32 s12, 16
	s_cbranch_scc1 .Ltopk_tail1
	s_or_b32 s9, s8, 0x1000000
	v_cmp_le_u32_e32 vcc, s9, v2
	s_bcnt1_i32_b64 s12, vcc
	s_cmp_gt_u32 s12, 15
	s_cselect_b32 s8, s9, s8
	s_cmp_eq_u32 s12, 16
	s_cbranch_scc1 .Ltopk_tail1
	s_or_b32 s9, s8, 0x800000
	v_cmp_le_u32_e32 vcc, s9, v2
	s_bcnt1_i32_b64 s12, vcc
	s_cmp_gt_u32 s12, 15
	s_cselect_b32 s8, s9, s8
	s_cmp_eq_u32 s12, 16
	s_cbranch_scc1 .Ltopk_tail1
	s_or_b32 s9, s8, 0x400000
	v_cmp_le_u32_e32 vcc, s9, v2
	s_bcnt1_i32_b64 s12, vcc
	s_cmp_gt_u32 s12, 15
	s_cselect_b32 s8, s9, s8
	s_cmp_eq_u32 s12, 16
	s_cbranch_scc1 .Ltopk_tail1
	s_or_b32 s9, s8, 0x200000
	v_cmp_le_u32_e32 vcc, s9, v2
	s_bcnt1_i32_b64 s12, vcc
	s_cmp_gt_u32 s12, 15
	s_cselect_b32 s8, s9, s8
	s_cmp_eq_u32 s12, 16
	s_cbranch_scc1 .Ltopk_tail1
	s_or_b32 s9, s8, 0x100000
	v_cmp_le_u32_e32 vcc, s9, v2
	s_bcnt1_i32_b64 s12, vcc
	s_cmp_gt_u32 s12, 15
	s_cselect_b32 s8, s9, s8
	s_cmp_eq_u32 s12, 16
	s_cbranch_scc1 .Ltopk_tail1
	s_or_b32 s9, s8, 0x80000
	v_cmp_le_u32_e32 vcc, s9, v2
	s_bcnt1_i32_b64 s12, vcc
	s_cmp_gt_u32 s12, 15
	s_cselect_b32 s8, s9, s8
	s_cmp_eq_u32 s12, 16
	s_cbranch_scc1 .Ltopk_tail1
	s_or_b32 s9, s8, 0x40000
	v_cmp_le_u32_e32 vcc, s9, v2
	s_bcnt1_i32_b64 s12, vcc
	s_cmp_gt_u32 s12, 15
	s_cselect_b32 s8, s9, s8
	s_cmp_eq_u32 s12, 16
	s_cbranch_scc1 .Ltopk_tail1
	s_or_b32 s9, s8, 0x20000
	v_cmp_le_u32_e32 vcc, s9, v2
	s_bcnt1_i32_b64 s12, vcc
	s_cmp_gt_u32 s12, 15
	s_cselect_b32 s8, s9, s8
	s_cmp_eq_u32 s12, 16
	s_cbranch_scc1 .Ltopk_tail1
	s_or_b32 s9, s8, 0x10000
	v_cmp_le_u32_e32 vcc, s9, v2
	s_bcnt1_i32_b64 s12, vcc
	s_cmp_gt_u32 s12, 15
	s_cselect_b32 s8, s9, s8
	s_cmp_eq_u32 s12, 16
	s_cbranch_scc1 .Ltopk_tail1
	s_or_b32 s9, s8, 0x8000
	v_cmp_le_u32_e32 vcc, s9, v2
	s_bcnt1_i32_b64 s12, vcc
	s_cmp_gt_u32 s12, 15
	s_cselect_b32 s8, s9, s8
	s_cmp_eq_u32 s12, 16
	s_cbranch_scc1 .Ltopk_tail1
	s_or_b32 s9, s8, 0x4000
	v_cmp_le_u32_e32 vcc, s9, v2
	s_bcnt1_i32_b64 s12, vcc
	s_cmp_gt_u32 s12, 15
	s_cselect_b32 s8, s9, s8
	s_cmp_eq_u32 s12, 16
	s_cbranch_scc1 .Ltopk_tail1
	s_or_b32 s9, s8, 0x2000
	v_cmp_le_u32_e32 vcc, s9, v2
	s_bcnt1_i32_b64 s12, vcc
	s_cmp_gt_u32 s12, 15
	s_cselect_b32 s8, s9, s8
	s_cmp_eq_u32 s12, 16
	s_cbranch_scc1 .Ltopk_tail1
	s_or_b32 s9, s8, 0x1000
	v_cmp_le_u32_e32 vcc, s9, v2
	s_bcnt1_i32_b64 s12, vcc
	s_cmp_gt_u32 s12, 15
	s_cselect_b32 s8, s9, s8
	s_cmp_eq_u32 s12, 16
	s_cbranch_scc1 .Ltopk_tail1
	s_or_b32 s9, s8, 0x800
	v_cmp_le_u32_e32 vcc, s9, v2
	s_bcnt1_i32_b64 s12, vcc
	s_cmp_gt_u32 s12, 15
	s_cselect_b32 s8, s9, s8
	s_cmp_eq_u32 s12, 16
	s_cbranch_scc1 .Ltopk_tail1
	s_or_b32 s9, s8, 0x400
	v_cmp_le_u32_e32 vcc, s9, v2
	s_bcnt1_i32_b64 s12, vcc
	s_cmp_gt_u32 s12, 15
	s_cselect_b32 s8, s9, s8
	s_cmp_eq_u32 s12, 16
	s_cbranch_scc1 .Ltopk_tail1
	s_or_b32 s9, s8, 0x200
	v_cmp_le_u32_e32 vcc, s9, v2
	s_bcnt1_i32_b64 s12, vcc
	s_cmp_gt_u32 s12, 15
	s_cselect_b32 s8, s9, s8
	s_cmp_eq_u32 s12, 16
	s_cbranch_scc1 .Ltopk_tail1
	s_or_b32 s9, s8, 0x100
	v_cmp_le_u32_e32 vcc, s9, v2
	s_bcnt1_i32_b64 s12, vcc
	s_cmp_gt_u32 s12, 15
	s_cselect_b32 s8, s9, s8
	s_cmp_eq_u32 s12, 16
	s_cbranch_scc1 .Ltopk_tail1
	s_or_b32 s9, s8, 0x80
	v_cmp_le_u32_e32 vcc, s9, v2
	s_bcnt1_i32_b64 s12, vcc
	s_cmp_gt_u32 s12, 15
	s_cselect_b32 s8, s9, s8
	s_cmp_eq_u32 s12, 16
	s_cbranch_scc1 .Ltopk_tail1
	s_or_b32 s9, s8, 64
	v_cmp_le_u32_e32 vcc, s9, v2
	s_bcnt1_i32_b64 s12, vcc
	s_cmp_gt_u32 s12, 15
	s_cselect_b32 s8, s9, s8
	s_cmp_eq_u32 s12, 16
	s_cbranch_scc1 .Ltopk_tail1
	s_or_b32 s9, s8, 32
	v_cmp_le_u32_e32 vcc, s9, v2
	s_bcnt1_i32_b64 s12, vcc
	s_cmp_gt_u32 s12, 15
	s_cselect_b32 s8, s9, s8
	s_cmp_eq_u32 s12, 16
	s_cbranch_scc1 .Ltopk_tail1
	s_or_b32 s9, s8, 16
	v_cmp_le_u32_e32 vcc, s9, v2
	s_bcnt1_i32_b64 s12, vcc
	s_cmp_gt_u32 s12, 15
	s_cselect_b32 s8, s9, s8
	s_cmp_eq_u32 s12, 16
	s_cbranch_scc1 .Ltopk_tail1
	s_or_b32 s9, s8, 8
	v_cmp_le_u32_e32 vcc, s9, v2
	s_bcnt1_i32_b64 s12, vcc
	s_cmp_gt_u32 s12, 15
	s_cselect_b32 s8, s9, s8
	s_cmp_eq_u32 s12, 16
	s_cbranch_scc1 .Ltopk_tail1
	s_or_b32 s9, s8, 4
	v_cmp_le_u32_e32 vcc, s9, v2
	s_bcnt1_i32_b64 s12, vcc
	s_cmp_gt_u32 s12, 15
	s_cselect_b32 s8, s9, s8
	s_cmp_eq_u32 s12, 16
	s_cbranch_scc1 .Ltopk_tail1
	s_or_b32 s9, s8, 2
	v_cmp_le_u32_e32 vcc, s9, v2
	s_bcnt1_i32_b64 s12, vcc
	s_cmp_gt_u32 s12, 15
	s_cselect_b32 s8, s9, s8
	s_cmp_eq_u32 s12, 16
	s_cbranch_scc1 .Ltopk_tail1
	s_or_b32 s9, s8, 1
	v_cmp_le_u32_e32 vcc, s9, v2
	s_bcnt1_i32_b64 s12, vcc
	s_cmp_gt_u32 s12, 15
	s_cselect_b32 s8, s9, s8
.Ltopk_tail1:
	v_cmp_eq_u32_e64 s[38:39], s8, v2
	v_cmp_lt_u32_e32 vcc, s8, v2
	v_cmp_lt_u32_e64 s[36:37], s8, v3
	v_cmp_eq_u32_e64 s[40:41], s8, v3
	v_and_b32_e32 v3, s38, v170
	s_bcnt1_i32_b64 s9, vcc
	s_bcnt1_i32_b64 s12, s[36:37]
	v_and_b32_e32 v2, s39, v163
	v_bcnt_u32_b32 v3, v3, 0
	v_and_b32_e32 v20, s40, v170
	s_add_i32 s9, s9, s12
	v_bcnt_u32_b32 v2, v2, v3
	v_and_b32_e32 v3, s41, v163
	v_bcnt_u32_b32 v20, v20, 0
	s_sub_i32 s12, 16, s9
	s_bcnt1_i32_b64 s8, s[38:39]
	v_bcnt_u32_b32 v3, v3, v20
	v_add_u32_e32 v3, s8, v3
	v_cmp_gt_i32_e64 s[42:43], s12, v2
	s_and_b64 s[8:9], s[38:39], s[42:43]
	v_cmp_gt_i32_e64 s[38:39], s12, v3
	s_and_b64 s[14:15], s[40:41], s[38:39]
	s_or_b64 s[8:9], vcc, s[8:9]
	v_cndmask_b32_e64 v2, 0, 1, s[8:9]
	s_or_b64 s[8:9], s[36:37], s[14:15]
	v_cmp_ne_u32_e64 s[12:13], 0, v2
	v_cndmask_b32_e64 v2, 0, 1, s[8:9]
	v_cmp_ne_u32_e32 vcc, 0, v2
	s_and_saveexec_b64 s[8:9], s[34:35]
	s_cbranch_execz .LBB0_156
	s_add_i32 s14, s3, 0
	s_add_i32 s14, s14, 0x22200
	v_mov_b32_e32 v20, s12
	v_mov_b32_e32 v21, s13
	v_mov_b32_e32 v22, vcc_lo
	v_mov_b32_e32 v23, vcc_hi
	v_mov_b32_e32 v2, s14
	ds_write_b128 v2, v[20:23]
	s_branch .LBB0_156

.Lattn_slc:
	s_mov_b64 exec, -1
	s_waitcnt vmcnt(0) lgkmcnt(0)
	v_lshrrev_b32_e32 v0, 6, v162
	s_nop 0
	v_readfirstlane_b32 s49, v0
	v_readlane_b32 s58, v255, 5
	v_readlane_b32 s59, v255, 6
	v_readlane_b32 s60, v255, 7
	v_readlane_b32 s61, v255, 8
	v_readlane_b32 s62, v254, 49
	v_readlane_b32 s63, v255, 0
	s_lshl_b32 s40, s49, 10
	s_add_i32 s41, s40, 0x8000
	s_add_i32 s48, s36, -1
	s_mov_b32 s43, 0
	s_mov_b32 s45, 0
	s_mov_b32 s38, 0
	v_and_b32_e32 v0, 31, v210
	v_lshrrev_b32_e32 v252, 5, v210
	v_bfe_u32 v248, v0, 1, 1
	v_xor_b32_e32 v248, v252, v248
	v_and_b32_e32 v249, 0x13, v0
	v_bfe_u32 v250, v0, 2, 1
	v_bfe_u32 v251, v0, 3, 1
	v_lshl_or_b32 v249, v250, 3, v249
	v_lshl_or_b32 v249, v251, 2, v249
	v_lshlrev_b32_e32 v249, 7, v249
	v_lshl_add_u32 v249, v248, 4, v249
	v_bfe_u32 v251, v0, 4, 1
	v_lshl_or_b32 v250, v251, 1, v250
	v_xor_b32_e32 v40, 0, v250
	v_lshl_add_u32 v40, v40, 5, v249
	v_xor_b32_e32 v41, 1, v250
	v_lshl_add_u32 v41, v41, 5, v249
	v_xor_b32_e32 v42, 2, v250
	v_lshl_add_u32 v42, v42, 5, v249
	v_xor_b32_e32 v96, 3, v250
	v_lshl_add_u32 v96, v96, 5, v249
	v_lshlrev_b32_e32 v249, 7, v0
	v_lshl_add_u32 v249, v248, 4, v249
	v_bfe_u32 v250, v0, 2, 2
	v_xor_b32_e32 v97, 0, v250
	v_lshl_add_u32 v97, v97, 5, v249
	v_xor_b32_e32 v98, 1, v250
	v_lshl_add_u32 v98, v98, 5, v249
	v_xor_b32_e32 v102, 2, v250
	v_lshl_add_u32 v102, v102, 5, v249
	v_xor_b32_e32 v103, 3, v250
	v_lshl_add_u32 v103, v103, 5, v249
	v_mov_b32_e32 v198, v20
	v_mov_b32_e32 v199, v21
	v_mov_b32_e32 v250, v22
	v_mov_b32_e32 v251, v23
	v_lshrrev_b32_e32 v0, 3, v210
	v_and_b32_e32 v248, 7, v210
	v_bfe_u32 v249, v210, 4, 1
	s_and_b32 s50, s49, 3
	s_lshl_b32 s50, s50, 1
	v_or_b32_e32 v249, s50, v249
	v_xor_b32_e32 v249, v248, v249
	s_lshl_b32 s51, s49, 11
	v_lshl_add_u32 v208, v0, 8, s51
	v_lshl_add_u32 v208, v249, 4, v208
	v_mov_b32_e32 v209, 0
	v_lshl_add_u64 v[106:107], s[58:59], 0, v[208:209]
	v_bfe_u32 v249, v210, 4, 2
	s_and_b32 s50, s49, 1
	s_lshl_b32 s50, s50, 2
	v_or_b32_e32 v249, s50, v249
	v_xor_b32_e32 v249, v248, v249
	s_lshl_b32 s51, s49, 17
	v_lshl_add_u32 v208, v0, 14, s51
	v_lshl_add_u32 v208, v249, 4, v208
	v_lshl_add_u64 v[122:123], s[60:61], 0, v[208:209]
	v_add_u32_e32 v160, s62, v172
	v_mov_b32_e32 v161, 0
	v_lshlrev_b64 v[160:161], 10, v[160:161]
	v_lshl_add_u64 v[160:161], v[160:161], 0, s[86:87]
	v_bfe_u32 v208, v210, 4, 1
	v_lshlrev_b32_e32 v208, 6, v208
	v_lshl_add_u32 v208, v252, 3, v208
	v_add_u32_e32 v208, s63, v208
	v_lshlrev_b32_e32 v208, 1, v208
	v_lshl_add_u64 v[160:161], v[208:209], 0, v[160:161]
	global_load_dwordx4 v[4:7], v[160:161], off
	global_load_dwordx4 v[8:11], v[160:161], off offset:32
	global_load_dwordx4 v[12:15], v[160:161], off offset:64
	global_load_dwordx4 v[16:19], v[160:161], off offset:96
	v_cmp_eq_u32_e64 s[50:51], 0, v252
	v_xor_b32_e32 v0, 0x80000000, v227
	v_cvt_pk_bf16_f32 v129, v0, 0
	v_cvt_pk_bf16_f32 v171, v197, 0
	v_mov_b32_e32 v0, 0x3f80
	v_cndmask_b32_e64 v129, 0, v129, s[50:51]
	v_cndmask_b32_e64 v171, 0, v171, s[50:51]
	v_cndmask_b32_e64 v204, 0, v0, s[50:51]
	v_mov_b32_e32 v205, 0
	v_mov_b32_e32 v245, 0
	v_mov_b32_e32 v206, 0
	v_mov_b32_e32 v246, 0
	v_mov_b32_e32 v207, 0
	v_mov_b32_e32 v247, 0
	s_lshl_b32 s50, s48, 6
	v_subrev_u32_e32 v120, s50, v172
	v_lshlrev_b32_e32 v0, 3, v252
	v_sub_u32_e32 v120, v120, v0
	v_mov_b32_e32 v176, 0
	v_mov_b32_e32 v177, 0
	v_mov_b32_e32 v178, 0
	v_mov_b32_e32 v179, 0
	v_mov_b32_e32 v180, 0
	v_mov_b32_e32 v181, 0
	v_mov_b32_e32 v182, 0
	v_mov_b32_e32 v183, 0
	v_mov_b32_e32 v184, 0
	v_mov_b32_e32 v185, 0
	v_mov_b32_e32 v186, 0
	v_mov_b32_e32 v187, 0
	v_mov_b32_e32 v188, 0
	v_mov_b32_e32 v189, 0
	v_mov_b32_e32 v190, 0
	v_mov_b32_e32 v191, 0
	v_mov_b32_e32 v228, 0
	v_mov_b32_e32 v229, 0
	v_mov_b32_e32 v230, 0
	v_mov_b32_e32 v231, 0
	v_mov_b32_e32 v232, 0
	v_mov_b32_e32 v233, 0
	v_mov_b32_e32 v234, 0
	v_mov_b32_e32 v235, 0
	v_mov_b32_e32 v236, 0
	v_mov_b32_e32 v237, 0
	v_mov_b32_e32 v238, 0
	v_mov_b32_e32 v239, 0
	v_mov_b32_e32 v240, 0
	v_mov_b32_e32 v241, 0
	v_mov_b32_e32 v242, 0
	v_mov_b32_e32 v243, 0
	v_mov_b32_e32 v68, 0
	v_mov_b32_e32 v69, 0
	v_mov_b32_e32 v70, 0
	v_mov_b32_e32 v71, 0
	v_mov_b32_e32 v72, 0
	v_mov_b32_e32 v73, 0
	v_mov_b32_e32 v74, 0
	v_mov_b32_e32 v75, 0
	v_mov_b32_e32 v76, 0
	v_mov_b32_e32 v77, 0
	v_mov_b32_e32 v78, 0
	v_mov_b32_e32 v79, 0
	v_mov_b32_e32 v80, 0
	v_mov_b32_e32 v81, 0
	v_mov_b32_e32 v82, 0
	v_mov_b32_e32 v83, 0
	v_mov_b32_e32 v132, 0
	v_mov_b32_e32 v133, 0
	v_mov_b32_e32 v134, 0
	v_mov_b32_e32 v135, 0
	v_mov_b32_e32 v136, 0
	v_mov_b32_e32 v137, 0
	v_mov_b32_e32 v138, 0
	v_mov_b32_e32 v139, 0
	v_mov_b32_e32 v140, 0
	v_mov_b32_e32 v141, 0
	v_mov_b32_e32 v142, 0
	v_mov_b32_e32 v143, 0
	v_mov_b32_e32 v144, 0
	v_mov_b32_e32 v145, 0
	v_mov_b32_e32 v146, 0
	v_mov_b32_e32 v147, 0
	v_mov_b32_e32 v174, 0
	v_mov_b32_e32 v193, 0
	v_and_b32_e32 v248, 1, v198
	v_cmp_eq_u32_e64 s[50:51], 1, v248
	s_nop 1
	v_cndmask_b32_e64 v244, v171, v129, s[50:51]
	s_waitcnt vmcnt(0)
	s_min_u32 s46, s48, 0
	s_lshl_b32 s42, s46, 14
	v_lshl_add_u64 v[160:161], s[42:43], 0, v[106:107]
	s_add_i32 m0, s40, 0x0
	s_nop 0
	global_load_lds_dwordx4 v[160:161], off
	s_min_u32 s46, s48, 1
	s_lshl_b32 s42, s46, 14
	v_lshl_add_u64 v[160:161], s[42:43], 0, v[106:107]
	s_add_i32 m0, s40, 0x2000
	s_nop 0
	global_load_lds_dwordx4 v[160:161], off
	s_min_u32 s47, s48, 0
	s_lshl_b32 s44, s47, 7
	v_lshl_add_u64 v[208:209], s[44:45], 0, v[122:123]
	s_add_i32 m0, s41, 0x6000
	s_nop 0
	global_load_lds_dwordx4 v[208:209], off
	s_min_u32 s46, s48, 2
	s_lshl_b32 s42, s46, 14
	v_lshl_add_u64 v[160:161], s[42:43], 0, v[106:107]
	s_add_i32 m0, s40, 0x4000
	s_nop 0
	global_load_lds_dwordx4 v[160:161], off
	s_min_u32 s47, s48, 0
	s_lshl_b32 s44, s47, 7
	v_lshl_add_u64 v[208:209], s[44:45], 0, v[122:123]
	s_add_i32 m0, s41, 0x0
	s_nop 0
	global_load_lds_dwordx4 v[208:209], off
	s_min_u32 s46, s48, 3
	s_lshl_b32 s42, s46, 14
	v_lshl_add_u64 v[160:161], s[42:43], 0, v[106:107]
	s_add_i32 m0, s40, 0x6000
	s_nop 0
	global_load_lds_dwordx4 v[160:161], off
	s_min_u32 s47, s48, 1
	s_lshl_b32 s44, s47, 7
	v_lshl_add_u64 v[208:209], s[44:45], 0, v[122:123]
	s_add_i32 m0, s41, 0x2000
	s_nop 0
	global_load_lds_dwordx4 v[208:209], off
	s_waitcnt vmcnt(6)
	s_barrier
	ds_read_b128 v[108:111], v40 offset:0
	ds_read_b128 v[112:115], v41 offset:0
	ds_read_b128 v[116:119], v42 offset:0
	ds_read_b128 v[124:127], v96 offset:0
	ds_read_b128 v[148:151], v40 offset:4096
	ds_read_b128 v[152:155], v41 offset:4096
	ds_read_b128 v[156:159], v42 offset:4096
	ds_read_b128 v[200:203], v96 offset:4096
.Lattn_it0:
	s_waitcnt vmcnt(4) lgkmcnt(0)
	s_barrier
	s_add_i32 s46, s38, 4
	s_min_u32 s46, s46, s48
	s_lshl_b32 s42, s46, 14
	s_add_i32 s47, s38, 2
	s_min_u32 s47, s47, s48
	s_lshl_b32 s44, s47, 7
	v_lshl_add_u64 v[160:161], s[42:43], 0, v[106:107]
	v_lshl_add_u64 v[208:209], s[44:45], 0, v[122:123]
	v_mfma_f32_32x32x16_bf16 v[20:35], v[204:207], v[244:247], 0
	v_cvt_pk_bf16_f32 v36, v68, v69
	v_add_f32_e32 v174, v174, v68
	v_add_f32_e32 v193, v193, v132
	v_cvt_pk_bf16_f32 v37, v70, v71
	v_add_f32_e32 v174, v174, v69
	v_mfma_f32_32x32x16_bf16 v[52:67], v[204:207], v[244:247], 0
	v_add_f32_e32 v193, v193, v133
	v_cvt_pk_bf16_f32 v38, v72, v73
	v_add_f32_e32 v174, v174, v70
	v_add_f32_e32 v193, v193, v134
	v_cvt_pk_bf16_f32 v39, v74, v75
	v_mfma_f32_32x32x16_bf16 v[20:35], v[108:111], v[4:7], v[20:35]
	v_add_f32_e32 v174, v174, v71
	v_add_f32_e32 v193, v193, v135
	v_cvt_pk_bf16_f32 v84, v76, v77
	v_add_f32_e32 v174, v174, v72
	v_add_f32_e32 v193, v193, v136
	ds_read_b128 v[108:111], v97 offset:57344
	s_add_i32 m0, s40, 0x0
	s_nop 0
	global_load_lds_dwordx4 v[160:161], off
	v_mfma_f32_32x32x16_bf16 v[20:35], v[112:115], v[8:11], v[20:35]
	v_cvt_pk_bf16_f32 v85, v78, v79
	v_add_f32_e32 v174, v174, v73
	v_add_f32_e32 v193, v193, v137
	v_cvt_pk_bf16_f32 v86, v80, v81
	v_add_f32_e32 v174, v174, v74
	ds_read_b128 v[112:115], v97 offset:61440
	v_mfma_f32_32x32x16_bf16 v[20:35], v[116:119], v[12:15], v[20:35]
	v_add_f32_e32 v193, v193, v138
	v_cvt_pk_bf16_f32 v87, v82, v83
	v_add_f32_e32 v174, v174, v75
	v_add_f32_e32 v193, v193, v139
	v_cvt_pk_bf16_f32 v88, v132, v133
	ds_read_b128 v[116:119], v98 offset:57344
	s_add_i32 m0, s41, 0x4000
	s_nop 0
	global_load_lds_dwordx4 v[208:209], off
	v_mfma_f32_32x32x16_bf16 v[20:35], v[124:127], v[16:19], v[20:35]
	v_add_f32_e32 v174, v174, v76
	v_add_f32_e32 v193, v193, v140
	v_cvt_pk_bf16_f32 v89, v134, v135
	v_add_f32_e32 v174, v174, v77
	v_add_f32_e32 v193, v193, v141
	ds_read_b128 v[124:127], v98 offset:61440
	v_mfma_f32_32x32x16_bf16 v[52:67], v[148:151], v[4:7], v[52:67]
	v_cvt_pk_bf16_f32 v90, v136, v137
	v_add_f32_e32 v174, v174, v78
	v_add_f32_e32 v193, v193, v142
	v_cvt_pk_bf16_f32 v91, v138, v139
	v_add_f32_e32 v174, v174, v79
	ds_read_b128 v[148:151], v102 offset:57344
	v_mfma_f32_32x32x16_bf16 v[52:67], v[152:155], v[8:11], v[52:67]
	v_add_f32_e32 v193, v193, v143
	v_cvt_pk_bf16_f32 v92, v140, v141
	v_add_f32_e32 v174, v174, v80
	v_add_f32_e32 v193, v193, v144
	v_cvt_pk_bf16_f32 v93, v142, v143
	ds_read_b128 v[152:155], v102 offset:61440
	v_mfma_f32_32x32x16_bf16 v[52:67], v[156:159], v[12:15], v[52:67]
	v_add_f32_e32 v174, v174, v81
	v_add_f32_e32 v193, v193, v145
	v_cvt_pk_bf16_f32 v94, v144, v145
	v_add_f32_e32 v174, v174, v82
	ds_read_b128 v[156:159], v103 offset:57344
	v_mfma_f32_32x32x16_bf16 v[52:67], v[200:203], v[16:19], v[52:67]
	v_add_f32_e32 v193, v193, v146
	v_cvt_pk_bf16_f32 v95, v146, v147
	v_add_f32_e32 v174, v174, v83
	v_add_f32_e32 v193, v193, v147
	ds_read_b128 v[200:203], v103 offset:61440
	s_waitcnt lgkmcnt(7)
	v_mfma_f32_32x32x16_bf16 v[176:191], v[108:111], v[36:39], v[176:191]
	v_exp_f32_e32 v20, v20
	v_exp_f32_e32 v21, v21
	v_exp_f32_e32 v22, v22
	v_exp_f32_e32 v23, v23
	ds_read_b128 v[108:111], v40 offset:8192
	s_waitcnt lgkmcnt(7)
	v_mfma_f32_32x32x16_bf16 v[228:243], v[112:115], v[36:39], v[228:243]
	v_exp_f32_e32 v24, v24
	v_exp_f32_e32 v25, v25
	v_exp_f32_e32 v26, v26
	v_exp_f32_e32 v27, v27
	ds_read_b128 v[112:115], v41 offset:8192
	s_waitcnt lgkmcnt(7)
	v_mfma_f32_32x32x16_bf16 v[176:191], v[116:119], v[84:87], v[176:191]
	v_exp_f32_e32 v28, v28
	v_exp_f32_e32 v29, v29
	v_exp_f32_e32 v30, v30
	v_exp_f32_e32 v31, v31
	ds_read_b128 v[116:119], v42 offset:8192
	s_waitcnt lgkmcnt(7)
	v_mfma_f32_32x32x16_bf16 v[228:243], v[124:127], v[84:87], v[228:243]
	v_exp_f32_e32 v32, v32
	v_exp_f32_e32 v33, v33
	v_exp_f32_e32 v34, v34
	v_exp_f32_e32 v35, v35
	ds_read_b128 v[124:127], v96 offset:8192
	s_waitcnt lgkmcnt(7)
	v_mfma_f32_32x32x16_bf16 v[176:191], v[148:151], v[88:91], v[176:191]
	v_exp_f32_e32 v52, v52
	v_exp_f32_e32 v53, v53
	v_exp_f32_e32 v54, v54
	v_exp_f32_e32 v55, v55
	ds_read_b128 v[148:151], v40 offset:12288
	s_waitcnt lgkmcnt(7)
	v_mfma_f32_32x32x16_bf16 v[228:243], v[152:155], v[88:91], v[228:243]
	v_exp_f32_e32 v56, v56
	v_exp_f32_e32 v57, v57
	v_exp_f32_e32 v58, v58
	v_exp_f32_e32 v59, v59
	ds_read_b128 v[152:155], v41 offset:12288
	s_waitcnt lgkmcnt(7)
	v_mfma_f32_32x32x16_bf16 v[176:191], v[156:159], v[92:95], v[176:191]
	v_exp_f32_e32 v60, v60
	v_exp_f32_e32 v61, v61
	v_exp_f32_e32 v62, v62
	v_exp_f32_e32 v63, v63
	ds_read_b128 v[156:159], v42 offset:12288
	s_waitcnt lgkmcnt(7)
	v_mfma_f32_32x32x16_bf16 v[228:243], v[200:203], v[92:95], v[228:243]
	v_exp_f32_e32 v64, v64
	v_exp_f32_e32 v65, v65
	v_exp_f32_e32 v66, v66
	v_exp_f32_e32 v67, v67
	ds_read_b128 v[200:203], v96 offset:12288
	s_cmp_eq_u32 s38, s48
	s_cbranch_scc0 .Lattn_nofix0
	v_cmp_le_i32_e64 s[50:51], 0, v120
	v_cmp_le_i32_e64 s[52:53], 1, v120
	v_cmp_le_i32_e64 s[56:57], 2, v120
	v_cndmask_b32_e64 v20, 0, v20, s[50:51]
	v_cmp_le_i32_e64 s[50:51], 3, v120
	v_cndmask_b32_e64 v21, 0, v21, s[52:53]
	v_cmp_le_i32_e64 s[52:53], 4, v120
	v_cndmask_b32_e64 v22, 0, v22, s[56:57]
	v_cmp_le_i32_e64 s[56:57], 5, v120
	v_cndmask_b32_e64 v23, 0, v23, s[50:51]
	v_cmp_le_i32_e64 s[50:51], 6, v120
	v_cndmask_b32_e64 v24, 0, v24, s[52:53]
	v_cmp_le_i32_e64 s[52:53], 7, v120
	v_cndmask_b32_e64 v25, 0, v25, s[56:57]
	v_cmp_le_i32_e64 s[56:57], 16, v120
	v_cndmask_b32_e64 v26, 0, v26, s[50:51]
	v_cmp_le_i32_e64 s[50:51], 17, v120
	v_cndmask_b32_e64 v27, 0, v27, s[52:53]
	v_cmp_le_i32_e64 s[52:53], 18, v120
	v_cndmask_b32_e64 v28, 0, v28, s[56:57]
	v_cmp_le_i32_e64 s[56:57], 19, v120
	v_cndmask_b32_e64 v29, 0, v29, s[50:51]
	v_cmp_le_i32_e64 s[50:51], 20, v120
	v_cndmask_b32_e64 v30, 0, v30, s[52:53]
	v_cmp_le_i32_e64 s[52:53], 21, v120
	v_cndmask_b32_e64 v31, 0, v31, s[56:57]
	v_cmp_le_i32_e64 s[56:57], 22, v120
	v_cndmask_b32_e64 v32, 0, v32, s[50:51]
	v_cmp_le_i32_e64 s[50:51], 23, v120
	v_cndmask_b32_e64 v33, 0, v33, s[52:53]
	v_cmp_le_i32_e64 s[52:53], 32, v120
	v_cndmask_b32_e64 v34, 0, v34, s[56:57]
	v_cmp_le_i32_e64 s[56:57], 33, v120
	v_cndmask_b32_e64 v35, 0, v35, s[50:51]
	v_cmp_le_i32_e64 s[50:51], 34, v120
	v_cndmask_b32_e64 v52, 0, v52, s[52:53]
	v_cmp_le_i32_e64 s[52:53], 35, v120
	v_cndmask_b32_e64 v53, 0, v53, s[56:57]
	v_cmp_le_i32_e64 s[56:57], 36, v120
	v_cndmask_b32_e64 v54, 0, v54, s[50:51]
	v_cmp_le_i32_e64 s[50:51], 37, v120
	v_cndmask_b32_e64 v55, 0, v55, s[52:53]
	v_cmp_le_i32_e64 s[52:53], 38, v120
	v_cndmask_b32_e64 v56, 0, v56, s[56:57]
	v_cmp_le_i32_e64 s[56:57], 39, v120
	v_cndmask_b32_e64 v57, 0, v57, s[50:51]
	v_cmp_le_i32_e64 s[50:51], 48, v120
	v_cndmask_b32_e64 v58, 0, v58, s[52:53]
	v_cmp_le_i32_e64 s[52:53], 49, v120
	v_cndmask_b32_e64 v59, 0, v59, s[56:57]
	v_cmp_le_i32_e64 s[56:57], 50, v120
	v_cndmask_b32_e64 v60, 0, v60, s[50:51]
	v_cmp_le_i32_e64 s[50:51], 51, v120
	v_cndmask_b32_e64 v61, 0, v61, s[52:53]
	v_cmp_le_i32_e64 s[52:53], 52, v120
	v_cndmask_b32_e64 v62, 0, v62, s[56:57]
	v_cmp_le_i32_e64 s[56:57], 53, v120
	v_cndmask_b32_e64 v63, 0, v63, s[50:51]
	v_cmp_le_i32_e64 s[50:51], 54, v120
	v_cndmask_b32_e64 v64, 0, v64, s[52:53]
	v_cmp_le_i32_e64 s[52:53], 55, v120
	v_cndmask_b32_e64 v65, 0, v65, s[56:57]
	s_nop 0
	v_cndmask_b32_e64 v66, 0, v66, s[50:51]
	s_nop 0
	v_cndmask_b32_e64 v67, 0, v67, s[52:53]
	s_nop 0
.Lattn_nofix0:
	s_cmp_eq_u32 s38, s36
	s_cbranch_scc1 .Lattn_done
	s_add_i32 s38, s38, 1
	s_cmp_eq_u32 s38, 64
	s_cbranch_scc0 .Lattn_nosw0
	v_mov_b32_e32 v198, v250
	v_mov_b32_e32 v199, v251
.Lattn_nosw0:
	v_lshrrev_b64 v[248:249], s38, v[198:199]
	v_and_b32_e32 v248, 1, v248
	v_cmp_eq_u32_e64 s[50:51], 1, v248
	s_nop 1
	v_cndmask_b32_e64 v244, v171, v129, s[50:51]
.Lattn_it1:
	s_waitcnt vmcnt(4) lgkmcnt(0)
	s_barrier
	s_add_i32 s46, s38, 4
	s_min_u32 s46, s46, s48
	s_lshl_b32 s42, s46, 14
	s_add_i32 s47, s38, 2
	s_min_u32 s47, s47, s48
	s_lshl_b32 s44, s47, 7
	v_lshl_add_u64 v[160:161], s[42:43], 0, v[106:107]
	v_lshl_add_u64 v[208:209], s[44:45], 0, v[122:123]
	v_mfma_f32_32x32x16_bf16 v[68:83], v[204:207], v[244:247], 0
	v_cvt_pk_bf16_f32 v36, v20, v21
	v_add_f32_e32 v174, v174, v20
	v_add_f32_e32 v193, v193, v52
	v_cvt_pk_bf16_f32 v37, v22, v23
	v_add_f32_e32 v174, v174, v21
	v_mfma_f32_32x32x16_bf16 v[132:147], v[204:207], v[244:247], 0
	v_add_f32_e32 v193, v193, v53
	v_cvt_pk_bf16_f32 v38, v24, v25
	v_add_f32_e32 v174, v174, v22
	v_add_f32_e32 v193, v193, v54
	v_cvt_pk_bf16_f32 v39, v26, v27
	v_mfma_f32_32x32x16_bf16 v[68:83], v[108:111], v[4:7], v[68:83]
	v_add_f32_e32 v174, v174, v23
	v_add_f32_e32 v193, v193, v55
	v_cvt_pk_bf16_f32 v84, v28, v29
	v_add_f32_e32 v174, v174, v24
	v_add_f32_e32 v193, v193, v56
	ds_read_b128 v[108:111], v97 offset:32768
	s_add_i32 m0, s40, 0x2000
	s_nop 0
	global_load_lds_dwordx4 v[160:161], off
	v_mfma_f32_32x32x16_bf16 v[68:83], v[112:115], v[8:11], v[68:83]
	v_cvt_pk_bf16_f32 v85, v30, v31
	v_add_f32_e32 v174, v174, v25
	v_add_f32_e32 v193, v193, v57
	v_cvt_pk_bf16_f32 v86, v32, v33
	v_add_f32_e32 v174, v174, v26
	ds_read_b128 v[112:115], v97 offset:36864
	v_mfma_f32_32x32x16_bf16 v[68:83], v[116:119], v[12:15], v[68:83]
	v_add_f32_e32 v193, v193, v58
	v_cvt_pk_bf16_f32 v87, v34, v35
	v_add_f32_e32 v174, v174, v27
	v_add_f32_e32 v193, v193, v59
	v_cvt_pk_bf16_f32 v88, v52, v53
	ds_read_b128 v[116:119], v98 offset:32768
	s_add_i32 m0, s41, 0x6000
	s_nop 0
	global_load_lds_dwordx4 v[208:209], off
	v_mfma_f32_32x32x16_bf16 v[68:83], v[124:127], v[16:19], v[68:83]
	v_add_f32_e32 v174, v174, v28
	v_add_f32_e32 v193, v193, v60
	v_cvt_pk_bf16_f32 v89, v54, v55
	v_add_f32_e32 v174, v174, v29
	v_add_f32_e32 v193, v193, v61
	ds_read_b128 v[124:127], v98 offset:36864
	v_mfma_f32_32x32x16_bf16 v[132:147], v[148:151], v[4:7], v[132:147]
	v_cvt_pk_bf16_f32 v90, v56, v57
	v_add_f32_e32 v174, v174, v30
	v_add_f32_e32 v193, v193, v62
	v_cvt_pk_bf16_f32 v91, v58, v59
	v_add_f32_e32 v174, v174, v31
	ds_read_b128 v[148:151], v102 offset:32768
	v_mfma_f32_32x32x16_bf16 v[132:147], v[152:155], v[8:11], v[132:147]
	v_add_f32_e32 v193, v193, v63
	v_cvt_pk_bf16_f32 v92, v60, v61
	v_add_f32_e32 v174, v174, v32
	v_add_f32_e32 v193, v193, v64
	v_cvt_pk_bf16_f32 v93, v62, v63
	ds_read_b128 v[152:155], v102 offset:36864
	v_mfma_f32_32x32x16_bf16 v[132:147], v[156:159], v[12:15], v[132:147]
	v_add_f32_e32 v174, v174, v33
	v_add_f32_e32 v193, v193, v65
	v_cvt_pk_bf16_f32 v94, v64, v65
	v_add_f32_e32 v174, v174, v34
	ds_read_b128 v[156:159], v103 offset:32768
	v_mfma_f32_32x32x16_bf16 v[132:147], v[200:203], v[16:19], v[132:147]
	v_add_f32_e32 v193, v193, v66
	v_cvt_pk_bf16_f32 v95, v66, v67
	v_add_f32_e32 v174, v174, v35
	v_add_f32_e32 v193, v193, v67
	ds_read_b128 v[200:203], v103 offset:36864
	s_waitcnt lgkmcnt(7)
	v_mfma_f32_32x32x16_bf16 v[176:191], v[108:111], v[36:39], v[176:191]
	v_exp_f32_e32 v68, v68
	v_exp_f32_e32 v69, v69
	v_exp_f32_e32 v70, v70
	v_exp_f32_e32 v71, v71
	ds_read_b128 v[108:111], v40 offset:16384
	s_waitcnt lgkmcnt(7)
	v_mfma_f32_32x32x16_bf16 v[228:243], v[112:115], v[36:39], v[228:243]
	v_exp_f32_e32 v72, v72
	v_exp_f32_e32 v73, v73
	v_exp_f32_e32 v74, v74
	v_exp_f32_e32 v75, v75
	ds_read_b128 v[112:115], v41 offset:16384
	s_waitcnt lgkmcnt(7)
	v_mfma_f32_32x32x16_bf16 v[176:191], v[116:119], v[84:87], v[176:191]
	v_exp_f32_e32 v76, v76
	v_exp_f32_e32 v77, v77
	v_exp_f32_e32 v78, v78
	v_exp_f32_e32 v79, v79
	ds_read_b128 v[116:119], v42 offset:16384
	s_waitcnt lgkmcnt(7)
	v_mfma_f32_32x32x16_bf16 v[228:243], v[124:127], v[84:87], v[228:243]
	v_exp_f32_e32 v80, v80
	v_exp_f32_e32 v81, v81
	v_exp_f32_e32 v82, v82
	v_exp_f32_e32 v83, v83
	ds_read_b128 v[124:127], v96 offset:16384
	s_waitcnt lgkmcnt(7)
	v_mfma_f32_32x32x16_bf16 v[176:191], v[148:151], v[88:91], v[176:191]
	v_exp_f32_e32 v132, v132
	v_exp_f32_e32 v133, v133
	v_exp_f32_e32 v134, v134
	v_exp_f32_e32 v135, v135
	ds_read_b128 v[148:151], v40 offset:20480
	s_waitcnt lgkmcnt(7)
	v_mfma_f32_32x32x16_bf16 v[228:243], v[152:155], v[88:91], v[228:243]
	v_exp_f32_e32 v136, v136
	v_exp_f32_e32 v137, v137
	v_exp_f32_e32 v138, v138
	v_exp_f32_e32 v139, v139
	ds_read_b128 v[152:155], v41 offset:20480
	s_waitcnt lgkmcnt(7)
	v_mfma_f32_32x32x16_bf16 v[176:191], v[156:159], v[92:95], v[176:191]
	v_exp_f32_e32 v140, v140
	v_exp_f32_e32 v141, v141
	v_exp_f32_e32 v142, v142
	v_exp_f32_e32 v143, v143
	ds_read_b128 v[156:159], v42 offset:20480
	s_waitcnt lgkmcnt(7)
	v_mfma_f32_32x32x16_bf16 v[228:243], v[200:203], v[92:95], v[228:243]
	v_exp_f32_e32 v144, v144
	v_exp_f32_e32 v145, v145
	v_exp_f32_e32 v146, v146
	v_exp_f32_e32 v147, v147
	ds_read_b128 v[200:203], v96 offset:20480
	s_cmp_eq_u32 s38, s48
	s_cbranch_scc0 .Lattn_nofix1
	v_cmp_le_i32_e64 s[50:51], 0, v120
	v_cmp_le_i32_e64 s[52:53], 1, v120
	v_cmp_le_i32_e64 s[56:57], 2, v120
	v_cndmask_b32_e64 v68, 0, v68, s[50:51]
	v_cmp_le_i32_e64 s[50:51], 3, v120
	v_cndmask_b32_e64 v69, 0, v69, s[52:53]
	v_cmp_le_i32_e64 s[52:53], 4, v120
	v_cndmask_b32_e64 v70, 0, v70, s[56:57]
	v_cmp_le_i32_e64 s[56:57], 5, v120
	v_cndmask_b32_e64 v71, 0, v71, s[50:51]
	v_cmp_le_i32_e64 s[50:51], 6, v120
	v_cndmask_b32_e64 v72, 0, v72, s[52:53]
	v_cmp_le_i32_e64 s[52:53], 7, v120
	v_cndmask_b32_e64 v73, 0, v73, s[56:57]
	v_cmp_le_i32_e64 s[56:57], 16, v120
	v_cndmask_b32_e64 v74, 0, v74, s[50:51]
	v_cmp_le_i32_e64 s[50:51], 17, v120
	v_cndmask_b32_e64 v75, 0, v75, s[52:53]
	v_cmp_le_i32_e64 s[52:53], 18, v120
	v_cndmask_b32_e64 v76, 0, v76, s[56:57]
	v_cmp_le_i32_e64 s[56:57], 19, v120
	v_cndmask_b32_e64 v77, 0, v77, s[50:51]
	v_cmp_le_i32_e64 s[50:51], 20, v120
	v_cndmask_b32_e64 v78, 0, v78, s[52:53]
	v_cmp_le_i32_e64 s[52:53], 21, v120
	v_cndmask_b32_e64 v79, 0, v79, s[56:57]
	v_cmp_le_i32_e64 s[56:57], 22, v120
	v_cndmask_b32_e64 v80, 0, v80, s[50:51]
	v_cmp_le_i32_e64 s[50:51], 23, v120
	v_cndmask_b32_e64 v81, 0, v81, s[52:53]
	v_cmp_le_i32_e64 s[52:53], 32, v120
	v_cndmask_b32_e64 v82, 0, v82, s[56:57]
	v_cmp_le_i32_e64 s[56:57], 33, v120
	v_cndmask_b32_e64 v83, 0, v83, s[50:51]
	v_cmp_le_i32_e64 s[50:51], 34, v120
	v_cndmask_b32_e64 v132, 0, v132, s[52:53]
	v_cmp_le_i32_e64 s[52:53], 35, v120
	v_cndmask_b32_e64 v133, 0, v133, s[56:57]
	v_cmp_le_i32_e64 s[56:57], 36, v120
	v_cndmask_b32_e64 v134, 0, v134, s[50:51]
	v_cmp_le_i32_e64 s[50:51], 37, v120
	v_cndmask_b32_e64 v135, 0, v135, s[52:53]
	v_cmp_le_i32_e64 s[52:53], 38, v120
	v_cndmask_b32_e64 v136, 0, v136, s[56:57]
	v_cmp_le_i32_e64 s[56:57], 39, v120
	v_cndmask_b32_e64 v137, 0, v137, s[50:51]
	v_cmp_le_i32_e64 s[50:51], 48, v120
	v_cndmask_b32_e64 v138, 0, v138, s[52:53]
	v_cmp_le_i32_e64 s[52:53], 49, v120
	v_cndmask_b32_e64 v139, 0, v139, s[56:57]
	v_cmp_le_i32_e64 s[56:57], 50, v120
	v_cndmask_b32_e64 v140, 0, v140, s[50:51]
	v_cmp_le_i32_e64 s[50:51], 51, v120
	v_cndmask_b32_e64 v141, 0, v141, s[52:53]
	v_cmp_le_i32_e64 s[52:53], 52, v120
	v_cndmask_b32_e64 v142, 0, v142, s[56:57]
	v_cmp_le_i32_e64 s[56:57], 53, v120
	v_cndmask_b32_e64 v143, 0, v143, s[50:51]
	v_cmp_le_i32_e64 s[50:51], 54, v120
	v_cndmask_b32_e64 v144, 0, v144, s[52:53]
	v_cmp_le_i32_e64 s[52:53], 55, v120
	v_cndmask_b32_e64 v145, 0, v145, s[56:57]
	s_nop 0
	v_cndmask_b32_e64 v146, 0, v146, s[50:51]
	s_nop 0
	v_cndmask_b32_e64 v147, 0, v147, s[52:53]
	s_nop 0

.Lattn_it2:
	s_waitcnt vmcnt(4) lgkmcnt(0)
	s_barrier
	s_add_i32 s46, s38, 4
	s_min_u32 s46, s46, s48
	s_lshl_b32 s42, s46, 14
	s_add_i32 s47, s38, 2
	s_min_u32 s47, s47, s48
	s_lshl_b32 s44, s47, 7
	v_lshl_add_u64 v[160:161], s[42:43], 0, v[106:107]
	v_lshl_add_u64 v[208:209], s[44:45], 0, v[122:123]
	v_mfma_f32_32x32x16_bf16 v[20:35], v[204:207], v[244:247], 0
	v_cvt_pk_bf16_f32 v36, v68, v69
	v_add_f32_e32 v174, v174, v68
	v_add_f32_e32 v193, v193, v132
	v_cvt_pk_bf16_f32 v37, v70, v71
	v_add_f32_e32 v174, v174, v69
	v_mfma_f32_32x32x16_bf16 v[52:67], v[204:207], v[244:247], 0
	v_add_f32_e32 v193, v193, v133
	v_cvt_pk_bf16_f32 v38, v72, v73
	v_add_f32_e32 v174, v174, v70
	v_add_f32_e32 v193, v193, v134
	v_cvt_pk_bf16_f32 v39, v74, v75
	v_mfma_f32_32x32x16_bf16 v[20:35], v[108:111], v[4:7], v[20:35]
	v_add_f32_e32 v174, v174, v71
	v_add_f32_e32 v193, v193, v135
	v_cvt_pk_bf16_f32 v84, v76, v77
	v_add_f32_e32 v174, v174, v72
	v_add_f32_e32 v193, v193, v136
	ds_read_b128 v[108:111], v97 offset:40960
	s_add_i32 m0, s40, 0x4000
	s_nop 0
	global_load_lds_dwordx4 v[160:161], off
	v_mfma_f32_32x32x16_bf16 v[20:35], v[112:115], v[8:11], v[20:35]
	v_cvt_pk_bf16_f32 v85, v78, v79
	v_add_f32_e32 v174, v174, v73
	v_add_f32_e32 v193, v193, v137
	v_cvt_pk_bf16_f32 v86, v80, v81
	v_add_f32_e32 v174, v174, v74
	ds_read_b128 v[112:115], v97 offset:45056
	v_mfma_f32_32x32x16_bf16 v[20:35], v[116:119], v[12:15], v[20:35]
	v_add_f32_e32 v193, v193, v138
	v_cvt_pk_bf16_f32 v87, v82, v83
	v_add_f32_e32 v174, v174, v75
	v_add_f32_e32 v193, v193, v139
	v_cvt_pk_bf16_f32 v88, v132, v133
	ds_read_b128 v[116:119], v98 offset:40960
	s_add_i32 m0, s41, 0x0
	s_nop 0
	global_load_lds_dwordx4 v[208:209], off
	v_mfma_f32_32x32x16_bf16 v[20:35], v[124:127], v[16:19], v[20:35]
	v_add_f32_e32 v174, v174, v76
	v_add_f32_e32 v193, v193, v140
	v_cvt_pk_bf16_f32 v89, v134, v135
	v_add_f32_e32 v174, v174, v77
	v_add_f32_e32 v193, v193, v141
	ds_read_b128 v[124:127], v98 offset:45056
	v_mfma_f32_32x32x16_bf16 v[52:67], v[148:151], v[4:7], v[52:67]
	v_cvt_pk_bf16_f32 v90, v136, v137
	v_add_f32_e32 v174, v174, v78
	v_add_f32_e32 v193, v193, v142
	v_cvt_pk_bf16_f32 v91, v138, v139
	v_add_f32_e32 v174, v174, v79
	ds_read_b128 v[148:151], v102 offset:40960
	v_mfma_f32_32x32x16_bf16 v[52:67], v[152:155], v[8:11], v[52:67]
	v_add_f32_e32 v193, v193, v143
	v_cvt_pk_bf16_f32 v92, v140, v141
	v_add_f32_e32 v174, v174, v80
	v_add_f32_e32 v193, v193, v144
	v_cvt_pk_bf16_f32 v93, v142, v143
	ds_read_b128 v[152:155], v102 offset:45056
	v_mfma_f32_32x32x16_bf16 v[52:67], v[156:159], v[12:15], v[52:67]
	v_add_f32_e32 v174, v174, v81
	v_add_f32_e32 v193, v193, v145
	v_cvt_pk_bf16_f32 v94, v144, v145
	v_add_f32_e32 v174, v174, v82
	ds_read_b128 v[156:159], v103 offset:40960
	v_mfma_f32_32x32x16_bf16 v[52:67], v[200:203], v[16:19], v[52:67]
	v_add_f32_e32 v193, v193, v146
	v_cvt_pk_bf16_f32 v95, v146, v147
	v_add_f32_e32 v174, v174, v83
	v_add_f32_e32 v193, v193, v147
	ds_read_b128 v[200:203], v103 offset:45056
	s_waitcnt lgkmcnt(7)
	v_mfma_f32_32x32x16_bf16 v[176:191], v[108:111], v[36:39], v[176:191]
	v_exp_f32_e32 v20, v20
	v_exp_f32_e32 v21, v21
	v_exp_f32_e32 v22, v22
	v_exp_f32_e32 v23, v23
	ds_read_b128 v[108:111], v40 offset:24576
	s_waitcnt lgkmcnt(7)
	v_mfma_f32_32x32x16_bf16 v[228:243], v[112:115], v[36:39], v[228:243]
	v_exp_f32_e32 v24, v24
	v_exp_f32_e32 v25, v25
	v_exp_f32_e32 v26, v26
	v_exp_f32_e32 v27, v27
	ds_read_b128 v[112:115], v41 offset:24576
	s_waitcnt lgkmcnt(7)
	v_mfma_f32_32x32x16_bf16 v[176:191], v[116:119], v[84:87], v[176:191]
	v_exp_f32_e32 v28, v28
	v_exp_f32_e32 v29, v29
	v_exp_f32_e32 v30, v30
	v_exp_f32_e32 v31, v31
	ds_read_b128 v[116:119], v42 offset:24576
	s_waitcnt lgkmcnt(7)
	v_mfma_f32_32x32x16_bf16 v[228:243], v[124:127], v[84:87], v[228:243]
	v_exp_f32_e32 v32, v32
	v_exp_f32_e32 v33, v33
	v_exp_f32_e32 v34, v34
	v_exp_f32_e32 v35, v35
	ds_read_b128 v[124:127], v96 offset:24576
	s_waitcnt lgkmcnt(7)
	v_mfma_f32_32x32x16_bf16 v[176:191], v[148:151], v[88:91], v[176:191]
	v_exp_f32_e32 v52, v52
	v_exp_f32_e32 v53, v53
	v_exp_f32_e32 v54, v54
	v_exp_f32_e32 v55, v55
	ds_read_b128 v[148:151], v40 offset:28672
	s_waitcnt lgkmcnt(7)
	v_mfma_f32_32x32x16_bf16 v[228:243], v[152:155], v[88:91], v[228:243]
	v_exp_f32_e32 v56, v56
	v_exp_f32_e32 v57, v57
	v_exp_f32_e32 v58, v58
	v_exp_f32_e32 v59, v59
	ds_read_b128 v[152:155], v41 offset:28672
	s_waitcnt lgkmcnt(7)
	v_mfma_f32_32x32x16_bf16 v[176:191], v[156:159], v[92:95], v[176:191]
	v_exp_f32_e32 v60, v60
	v_exp_f32_e32 v61, v61
	v_exp_f32_e32 v62, v62
	v_exp_f32_e32 v63, v63
	ds_read_b128 v[156:159], v42 offset:28672
	s_waitcnt lgkmcnt(7)
	v_mfma_f32_32x32x16_bf16 v[228:243], v[200:203], v[92:95], v[228:243]
	v_exp_f32_e32 v64, v64
	v_exp_f32_e32 v65, v65
	v_exp_f32_e32 v66, v66
	v_exp_f32_e32 v67, v67
	ds_read_b128 v[200:203], v96 offset:28672
	s_cmp_eq_u32 s38, s48
	s_cbranch_scc0 .Lattn_nofix2
	v_cmp_le_i32_e64 s[50:51], 0, v120
	v_cmp_le_i32_e64 s[52:53], 1, v120
	v_cmp_le_i32_e64 s[56:57], 2, v120
	v_cndmask_b32_e64 v20, 0, v20, s[50:51]
	v_cmp_le_i32_e64 s[50:51], 3, v120
	v_cndmask_b32_e64 v21, 0, v21, s[52:53]
	v_cmp_le_i32_e64 s[52:53], 4, v120
	v_cndmask_b32_e64 v22, 0, v22, s[56:57]
	v_cmp_le_i32_e64 s[56:57], 5, v120
	v_cndmask_b32_e64 v23, 0, v23, s[50:51]
	v_cmp_le_i32_e64 s[50:51], 6, v120
	v_cndmask_b32_e64 v24, 0, v24, s[52:53]
	v_cmp_le_i32_e64 s[52:53], 7, v120
	v_cndmask_b32_e64 v25, 0, v25, s[56:57]
	v_cmp_le_i32_e64 s[56:57], 16, v120
	v_cndmask_b32_e64 v26, 0, v26, s[50:51]
	v_cmp_le_i32_e64 s[50:51], 17, v120
	v_cndmask_b32_e64 v27, 0, v27, s[52:53]
	v_cmp_le_i32_e64 s[52:53], 18, v120
	v_cndmask_b32_e64 v28, 0, v28, s[56:57]
	v_cmp_le_i32_e64 s[56:57], 19, v120
	v_cndmask_b32_e64 v29, 0, v29, s[50:51]
	v_cmp_le_i32_e64 s[50:51], 20, v120
	v_cndmask_b32_e64 v30, 0, v30, s[52:53]
	v_cmp_le_i32_e64 s[52:53], 21, v120
	v_cndmask_b32_e64 v31, 0, v31, s[56:57]
	v_cmp_le_i32_e64 s[56:57], 22, v120
	v_cndmask_b32_e64 v32, 0, v32, s[50:51]
	v_cmp_le_i32_e64 s[50:51], 23, v120
	v_cndmask_b32_e64 v33, 0, v33, s[52:53]
	v_cmp_le_i32_e64 s[52:53], 32, v120
	v_cndmask_b32_e64 v34, 0, v34, s[56:57]
	v_cmp_le_i32_e64 s[56:57], 33, v120
	v_cndmask_b32_e64 v35, 0, v35, s[50:51]
	v_cmp_le_i32_e64 s[50:51], 34, v120
	v_cndmask_b32_e64 v52, 0, v52, s[52:53]
	v_cmp_le_i32_e64 s[52:53], 35, v120
	v_cndmask_b32_e64 v53, 0, v53, s[56:57]
	v_cmp_le_i32_e64 s[56:57], 36, v120
	v_cndmask_b32_e64 v54, 0, v54, s[50:51]
	v_cmp_le_i32_e64 s[50:51], 37, v120
	v_cndmask_b32_e64 v55, 0, v55, s[52:53]
	v_cmp_le_i32_e64 s[52:53], 38, v120
	v_cndmask_b32_e64 v56, 0, v56, s[56:57]
	v_cmp_le_i32_e64 s[56:57], 39, v120
	v_cndmask_b32_e64 v57, 0, v57, s[50:51]
	v_cmp_le_i32_e64 s[50:51], 48, v120
	v_cndmask_b32_e64 v58, 0, v58, s[52:53]
	v_cmp_le_i32_e64 s[52:53], 49, v120
	v_cndmask_b32_e64 v59, 0, v59, s[56:57]
	v_cmp_le_i32_e64 s[56:57], 50, v120
	v_cndmask_b32_e64 v60, 0, v60, s[50:51]
	v_cmp_le_i32_e64 s[50:51], 51, v120
	v_cndmask_b32_e64 v61, 0, v61, s[52:53]
	v_cmp_le_i32_e64 s[52:53], 52, v120
	v_cndmask_b32_e64 v62, 0, v62, s[56:57]
	v_cmp_le_i32_e64 s[56:57], 53, v120
	v_cndmask_b32_e64 v63, 0, v63, s[50:51]
	v_cmp_le_i32_e64 s[50:51], 54, v120
	v_cndmask_b32_e64 v64, 0, v64, s[52:53]
	v_cmp_le_i32_e64 s[52:53], 55, v120
	v_cndmask_b32_e64 v65, 0, v65, s[56:57]
	s_nop 0
	v_cndmask_b32_e64 v66, 0, v66, s[50:51]
	s_nop 0
	v_cndmask_b32_e64 v67, 0, v67, s[52:53]
	s_nop 0

.Lattn_it3:
	s_waitcnt vmcnt(4) lgkmcnt(0)
	s_barrier
	s_add_i32 s46, s38, 4
	s_min_u32 s46, s46, s48
	s_lshl_b32 s42, s46, 14
	s_add_i32 s47, s38, 2
	s_min_u32 s47, s47, s48
	s_lshl_b32 s44, s47, 7
	v_lshl_add_u64 v[160:161], s[42:43], 0, v[106:107]
	v_lshl_add_u64 v[208:209], s[44:45], 0, v[122:123]
	v_mfma_f32_32x32x16_bf16 v[68:83], v[204:207], v[244:247], 0
	v_cvt_pk_bf16_f32 v36, v20, v21
	v_add_f32_e32 v174, v174, v20
	v_add_f32_e32 v193, v193, v52
	v_cvt_pk_bf16_f32 v37, v22, v23
	v_add_f32_e32 v174, v174, v21
	v_mfma_f32_32x32x16_bf16 v[132:147], v[204:207], v[244:247], 0
	v_add_f32_e32 v193, v193, v53
	v_cvt_pk_bf16_f32 v38, v24, v25
	v_add_f32_e32 v174, v174, v22
	v_add_f32_e32 v193, v193, v54
	v_cvt_pk_bf16_f32 v39, v26, v27
	v_mfma_f32_32x32x16_bf16 v[68:83], v[108:111], v[4:7], v[68:83]
	v_add_f32_e32 v174, v174, v23
	v_add_f32_e32 v193, v193, v55
	v_cvt_pk_bf16_f32 v84, v28, v29
	v_add_f32_e32 v174, v174, v24
	v_add_f32_e32 v193, v193, v56
	ds_read_b128 v[108:111], v97 offset:49152
	s_add_i32 m0, s40, 0x6000
	s_nop 0
	global_load_lds_dwordx4 v[160:161], off
	v_mfma_f32_32x32x16_bf16 v[68:83], v[112:115], v[8:11], v[68:83]
	v_cvt_pk_bf16_f32 v85, v30, v31
	v_add_f32_e32 v174, v174, v25
	v_add_f32_e32 v193, v193, v57
	v_cvt_pk_bf16_f32 v86, v32, v33
	v_add_f32_e32 v174, v174, v26
	ds_read_b128 v[112:115], v97 offset:53248
	v_mfma_f32_32x32x16_bf16 v[68:83], v[116:119], v[12:15], v[68:83]
	v_add_f32_e32 v193, v193, v58
	v_cvt_pk_bf16_f32 v87, v34, v35
	v_add_f32_e32 v174, v174, v27
	v_add_f32_e32 v193, v193, v59
	v_cvt_pk_bf16_f32 v88, v52, v53
	ds_read_b128 v[116:119], v98 offset:49152
	s_add_i32 m0, s41, 0x2000
	s_nop 0
	global_load_lds_dwordx4 v[208:209], off
	v_mfma_f32_32x32x16_bf16 v[68:83], v[124:127], v[16:19], v[68:83]
	v_add_f32_e32 v174, v174, v28
	v_add_f32_e32 v193, v193, v60
	v_cvt_pk_bf16_f32 v89, v54, v55
	v_add_f32_e32 v174, v174, v29
	v_add_f32_e32 v193, v193, v61
	ds_read_b128 v[124:127], v98 offset:53248
	v_mfma_f32_32x32x16_bf16 v[132:147], v[148:151], v[4:7], v[132:147]
	v_cvt_pk_bf16_f32 v90, v56, v57
	v_add_f32_e32 v174, v174, v30
	v_add_f32_e32 v193, v193, v62
	v_cvt_pk_bf16_f32 v91, v58, v59
	v_add_f32_e32 v174, v174, v31
	ds_read_b128 v[148:151], v102 offset:49152
	v_mfma_f32_32x32x16_bf16 v[132:147], v[152:155], v[8:11], v[132:147]
	v_add_f32_e32 v193, v193, v63
	v_cvt_pk_bf16_f32 v92, v60, v61
	v_add_f32_e32 v174, v174, v32
	v_add_f32_e32 v193, v193, v64
	v_cvt_pk_bf16_f32 v93, v62, v63
	ds_read_b128 v[152:155], v102 offset:53248
	v_mfma_f32_32x32x16_bf16 v[132:147], v[156:159], v[12:15], v[132:147]
	v_add_f32_e32 v174, v174, v33
	v_add_f32_e32 v193, v193, v65
	v_cvt_pk_bf16_f32 v94, v64, v65
	v_add_f32_e32 v174, v174, v34
	ds_read_b128 v[156:159], v103 offset:49152
	v_mfma_f32_32x32x16_bf16 v[132:147], v[200:203], v[16:19], v[132:147]
	v_add_f32_e32 v193, v193, v66
	v_cvt_pk_bf16_f32 v95, v66, v67
	v_add_f32_e32 v174, v174, v35
	v_add_f32_e32 v193, v193, v67
	ds_read_b128 v[200:203], v103 offset:53248
	s_waitcnt lgkmcnt(7)
	v_mfma_f32_32x32x16_bf16 v[176:191], v[108:111], v[36:39], v[176:191]
	v_exp_f32_e32 v68, v68
	v_exp_f32_e32 v69, v69
	v_exp_f32_e32 v70, v70
	v_exp_f32_e32 v71, v71
	ds_read_b128 v[108:111], v40 offset:0
	s_waitcnt lgkmcnt(7)
	v_mfma_f32_32x32x16_bf16 v[228:243], v[112:115], v[36:39], v[228:243]
	v_exp_f32_e32 v72, v72
	v_exp_f32_e32 v73, v73
	v_exp_f32_e32 v74, v74
	v_exp_f32_e32 v75, v75
	ds_read_b128 v[112:115], v41 offset:0
	s_waitcnt lgkmcnt(7)
	v_mfma_f32_32x32x16_bf16 v[176:191], v[116:119], v[84:87], v[176:191]
	v_exp_f32_e32 v76, v76
	v_exp_f32_e32 v77, v77
	v_exp_f32_e32 v78, v78
	v_exp_f32_e32 v79, v79
	ds_read_b128 v[116:119], v42 offset:0
	s_waitcnt lgkmcnt(7)
	v_mfma_f32_32x32x16_bf16 v[228:243], v[124:127], v[84:87], v[228:243]
	v_exp_f32_e32 v80, v80
	v_exp_f32_e32 v81, v81
	v_exp_f32_e32 v82, v82
	v_exp_f32_e32 v83, v83
	ds_read_b128 v[124:127], v96 offset:0
	s_waitcnt lgkmcnt(7)
	v_mfma_f32_32x32x16_bf16 v[176:191], v[148:151], v[88:91], v[176:191]
	v_exp_f32_e32 v132, v132
	v_exp_f32_e32 v133, v133
	v_exp_f32_e32 v134, v134
	v_exp_f32_e32 v135, v135
	ds_read_b128 v[148:151], v40 offset:4096
	s_waitcnt lgkmcnt(7)
	v_mfma_f32_32x32x16_bf16 v[228:243], v[152:155], v[88:91], v[228:243]
	v_exp_f32_e32 v136, v136
	v_exp_f32_e32 v137, v137
	v_exp_f32_e32 v138, v138
	v_exp_f32_e32 v139, v139
	ds_read_b128 v[152:155], v41 offset:4096
	s_waitcnt lgkmcnt(7)
	v_mfma_f32_32x32x16_bf16 v[176:191], v[156:159], v[92:95], v[176:191]
	v_exp_f32_e32 v140, v140
	v_exp_f32_e32 v141, v141
	v_exp_f32_e32 v142, v142
	v_exp_f32_e32 v143, v143
	ds_read_b128 v[156:159], v42 offset:4096
	s_waitcnt lgkmcnt(7)
	v_mfma_f32_32x32x16_bf16 v[228:243], v[200:203], v[92:95], v[228:243]
	v_exp_f32_e32 v144, v144
	v_exp_f32_e32 v145, v145
	v_exp_f32_e32 v146, v146
	v_exp_f32_e32 v147, v147
	ds_read_b128 v[200:203], v96 offset:4096
	s_cmp_eq_u32 s38, s48
	s_cbranch_scc0 .Lattn_nofix3
	v_cmp_le_i32_e64 s[50:51], 0, v120
	v_cmp_le_i32_e64 s[52:53], 1, v120
	v_cmp_le_i32_e64 s[56:57], 2, v120
	v_cndmask_b32_e64 v68, 0, v68, s[50:51]
	v_cmp_le_i32_e64 s[50:51], 3, v120
	v_cndmask_b32_e64 v69, 0, v69, s[52:53]
	v_cmp_le_i32_e64 s[52:53], 4, v120
	v_cndmask_b32_e64 v70, 0, v70, s[56:57]
	v_cmp_le_i32_e64 s[56:57], 5, v120
	v_cndmask_b32_e64 v71, 0, v71, s[50:51]
	v_cmp_le_i32_e64 s[50:51], 6, v120
	v_cndmask_b32_e64 v72, 0, v72, s[52:53]
	v_cmp_le_i32_e64 s[52:53], 7, v120
	v_cndmask_b32_e64 v73, 0, v73, s[56:57]
	v_cmp_le_i32_e64 s[56:57], 16, v120
	v_cndmask_b32_e64 v74, 0, v74, s[50:51]
	v_cmp_le_i32_e64 s[50:51], 17, v120
	v_cndmask_b32_e64 v75, 0, v75, s[52:53]
	v_cmp_le_i32_e64 s[52:53], 18, v120
	v_cndmask_b32_e64 v76, 0, v76, s[56:57]
	v_cmp_le_i32_e64 s[56:57], 19, v120
	v_cndmask_b32_e64 v77, 0, v77, s[50:51]
	v_cmp_le_i32_e64 s[50:51], 20, v120
	v_cndmask_b32_e64 v78, 0, v78, s[52:53]
	v_cmp_le_i32_e64 s[52:53], 21, v120
	v_cndmask_b32_e64 v79, 0, v79, s[56:57]
	v_cmp_le_i32_e64 s[56:57], 22, v120
	v_cndmask_b32_e64 v80, 0, v80, s[50:51]
	v_cmp_le_i32_e64 s[50:51], 23, v120
	v_cndmask_b32_e64 v81, 0, v81, s[52:53]
	v_cmp_le_i32_e64 s[52:53], 32, v120
	v_cndmask_b32_e64 v82, 0, v82, s[56:57]
	v_cmp_le_i32_e64 s[56:57], 33, v120
	v_cndmask_b32_e64 v83, 0, v83, s[50:51]
	v_cmp_le_i32_e64 s[50:51], 34, v120
	v_cndmask_b32_e64 v132, 0, v132, s[52:53]
	v_cmp_le_i32_e64 s[52:53], 35, v120
	v_cndmask_b32_e64 v133, 0, v133, s[56:57]
	v_cmp_le_i32_e64 s[56:57], 36, v120
	v_cndmask_b32_e64 v134, 0, v134, s[50:51]
	v_cmp_le_i32_e64 s[50:51], 37, v120
	v_cndmask_b32_e64 v135, 0, v135, s[52:53]
	v_cmp_le_i32_e64 s[52:53], 38, v120
	v_cndmask_b32_e64 v136, 0, v136, s[56:57]
	v_cmp_le_i32_e64 s[56:57], 39, v120
	v_cndmask_b32_e64 v137, 0, v137, s[50:51]
	v_cmp_le_i32_e64 s[50:51], 48, v120
	v_cndmask_b32_e64 v138, 0, v138, s[52:53]
	v_cmp_le_i32_e64 s[52:53], 49, v120
	v_cndmask_b32_e64 v139, 0, v139, s[56:57]
	v_cmp_le_i32_e64 s[56:57], 50, v120
	v_cndmask_b32_e64 v140, 0, v140, s[50:51]
	v_cmp_le_i32_e64 s[50:51], 51, v120
	v_cndmask_b32_e64 v141, 0, v141, s[52:53]
	v_cmp_le_i32_e64 s[52:53], 52, v120
	v_cndmask_b32_e64 v142, 0, v142, s[56:57]
	v_cmp_le_i32_e64 s[56:57], 53, v120
	v_cndmask_b32_e64 v143, 0, v143, s[50:51]
	v_cmp_le_i32_e64 s[50:51], 54, v120
	v_cndmask_b32_e64 v144, 0, v144, s[52:53]
	v_cmp_le_i32_e64 s[52:53], 55, v120
	v_cndmask_b32_e64 v145, 0, v145, s[56:57]
	s_nop 0
	v_cndmask_b32_e64 v146, 0, v146, s[50:51]
	s_nop 0
	v_cndmask_b32_e64 v147, 0, v147, s[52:53]
	s_nop 0

.Lattn_nosw3:
	v_lshrrev_b64 v[248:249], s38, v[198:199]
	v_and_b32_e32 v248, 1, v248
	v_cmp_eq_u32_e64 s[50:51], 1, v248
	s_nop 1
	v_cndmask_b32_e64 v244, v171, v129, s[50:51]
	s_branch .Lattn_it0
.Lattn_done:
	s_waitcnt vmcnt(0) lgkmcnt(0)
	s_barrier
	v_add_u32_e32 v160, s62, v172
	v_mov_b32_e32 v161, 0
	v_lshlrev_b64 v[160:161], 10, v[160:161]
	v_lshl_add_u64 v[160:161], v[164:165], 0, v[160:161]
	s_mov_b32 s50, s63
	s_mov_b32 s51, 0
	v_lshl_add_u64 v[160:161], s[50:51], 1, v[160:161]
	global_load_dwordx4 v[4:7], v[160:161], off
	global_load_dwordx4 v[8:11], v[160:161], off offset:64
	global_load_dwordx4 v[12:15], v[160:161], off offset:128
	global_load_dwordx4 v[16:19], v[160:161], off offset:192
	v_add_f32_e32 v174, v174, v193
	v_and_b32_e32 v0, 31, v210
	v_lshrrev_b32_e32 v252, 5, v210
	s_mul_i32 s50, s49, 0x2300
	v_mul_u32_u24_e32 v248, 0x110, v0
	v_lshl_add_u32 v248, v252, 4, v248
	v_add_u32_e32 v248, s50, v248
	ds_write_b128 v248, v[176:179] offset:0
	ds_write_b128 v248, v[180:183] offset:32
	ds_write_b128 v248, v[184:187] offset:64
	ds_write_b128 v248, v[188:191] offset:96
	ds_write_b128 v248, v[228:231] offset:128
	ds_write_b128 v248, v[232:235] offset:160
	ds_write_b128 v248, v[236:239] offset:192
	ds_write_b128 v248, v[240:243] offset:224
	v_lshl_add_u32 v249, v0, 1, v252
	v_lshlrev_b32_e32 v249, 2, v249
	v_add_u32_e32 v249, s50, v249
	ds_write_b32 v249, v174 offset:8704
	s_waitcnt lgkmcnt(0)
	v_lshrrev_b32_e32 v252, 4, v210
	v_mul_u32_u24_e32 v248, 0x110, v211
	v_lshl_add_u32 v248, v252, 4, v248
	v_add_u32_e32 v248, s50, v248
	ds_read_b128 v[64:67], v248 offset:0
	ds_read_b128 v[56:59], v248 offset:64
	ds_read_b128 v[52:55], v248 offset:128
	ds_read_b128 v[60:63], v248 offset:192
	ds_read_b128 v[36:39], v248 offset:4352
	ds_read_b128 v[32:35], v248 offset:4416
	ds_read_b128 v[24:27], v248 offset:4480
	ds_read_b128 v[28:31], v248 offset:4544
	v_and_b32_e32 v0, 1, v252
	v_lshl_add_u32 v0, v211, 1, v0
	v_lshlrev_b32_e32 v0, 2, v0
	v_add_u32_e32 v0, s50, v0
	ds_read_b32 v112, v0 offset:8704
	ds_read_b32 v113, v0 offset:8832
	v_cmp_gt_u32_e64 s[50:51], 2, v252
	s_waitcnt lgkmcnt(0)
	s_nop 1
	v_cndmask_b32_e64 v112, 0, v112, s[50:51]
	v_cndmask_b32_e64 v113, 0, v113, s[50:51]
	v_mov_b64_e32 v[156:157], 0xff
	v_mov_b64_e32 v[158:159], 0x580
	v_mov_b64_e32 v[160:161], 0x57f
	v_mov_b32_e32 v188, 0x358637bd
	v_mov_b32_e32 v189, 0x3dcccccd
	v_mov_b32_e32 v190, 0x3c0881c4
	v_mov_b32_e32 v191, 0xbab64f3b
	v_mov_b32_e32 v201, 0x7fc00000
	v_mov_b32_e32 v202, 0x3e38aa3b
	v_mov_b32_e32 v203, 0xb0
	v_mov_b32_e32 v204, 0xb1
	v_mov_b32_e32 v205, 0x410
	v_mov_b32_e32 v206, 0x820
	v_mov_b32_e32 v207, 0xc30
	v_mov_b32_e32 v208, 0x580000
	v_mov_b32_e32 v209, 0xb00000
	v_not_b32_e32 v200, 31
	s_waitcnt vmcnt(0)
	s_barrier
	s_cmp_eq_u32 s37, 1
	s_cbranch_scc1 .Lattn_ret1

.LBB0_236:
	s_or_b64 exec, exec, s[2:3]
	s_waitcnt lgkmcnt(0)
	v_add_f32_e32 v3, v3, v20
	v_cmp_ne_u32_e32 vcc, s12, v219
	s_brev_b32 s3, -4
	s_nop 0
	v_cndmask_b32_e32 v3, v196, v3, vcc
	v_cmp_ge_i32_e32 vcc, s12, v219
	s_nop 1
	v_cndmask_b32_e32 v3, 0, v3, vcc
	v_cmp_lt_u32_e32 vcc, s3, v2
	s_bcnt1_i32_b64 s2, vcc
	v_cmp_lt_u32_e32 vcc, s3, v3
	s_bcnt1_i32_b64 s3, vcc
	s_add_i32 s3, s3, s2
	s_cmp_gt_u32 s3, 15
	s_cselect_b32 s2, 2.0, 0
	s_or_b32 s3, s2, 0x20000000
	v_cmp_le_u32_e64 s[36:37], s3, v2
	v_cmp_le_u32_e32 vcc, s3, v3
	s_bcnt1_i32_b64 s12, s[36:37]
	s_bcnt1_i32_b64 s13, vcc
	s_add_i32 s13, s13, s12
	s_cmp_gt_u32 s13, 15
	s_cselect_b32 s2, s3, s2
	s_cmp_eq_u32 s13, 16
	s_cbranch_scc1 .Ltopk_tail2
	s_or_b32 s3, s2, 0x10000000
	v_cmp_le_u32_e64 s[36:37], s3, v2
	v_cmp_le_u32_e32 vcc, s3, v3
	s_bcnt1_i32_b64 s12, s[36:37]
	s_bcnt1_i32_b64 s13, vcc
	s_add_i32 s13, s13, s12
	s_cmp_gt_u32 s13, 15
	s_cselect_b32 s2, s3, s2
	s_cmp_eq_u32 s13, 16
	s_cbranch_scc1 .Ltopk_tail2
	s_or_b32 s3, s2, 0x8000000
	v_cmp_le_u32_e64 s[36:37], s3, v2
	v_cmp_le_u32_e32 vcc, s3, v3
	s_bcnt1_i32_b64 s12, s[36:37]
	s_bcnt1_i32_b64 s13, vcc
	s_add_i32 s13, s13, s12
	s_cmp_gt_u32 s13, 15
	s_cselect_b32 s2, s3, s2
	s_cmp_eq_u32 s13, 16
	s_cbranch_scc1 .Ltopk_tail2
	s_or_b32 s3, s2, 0x4000000
	v_cmp_le_u32_e64 s[36:37], s3, v2
	v_cmp_le_u32_e32 vcc, s3, v3
	s_bcnt1_i32_b64 s12, s[36:37]
	s_bcnt1_i32_b64 s13, vcc
	s_add_i32 s13, s13, s12
	s_cmp_gt_u32 s13, 15
	s_cselect_b32 s2, s3, s2
	s_cmp_eq_u32 s13, 16
	s_cbranch_scc1 .Ltopk_tail2
	s_or_b32 s3, s2, 0x2000000
	v_cmp_le_u32_e64 s[36:37], s3, v2
	v_cmp_le_u32_e32 vcc, s3, v3
	s_bcnt1_i32_b64 s12, s[36:37]
	s_bcnt1_i32_b64 s13, vcc
	s_add_i32 s13, s13, s12
	s_cmp_gt_u32 s13, 15
	s_cselect_b32 s2, s3, s2
	s_cmp_eq_u32 s13, 16
	s_cbranch_scc1 .Ltopk_tail2
	s_or_b32 s3, s2, 0x1000000
	v_cmp_le_u32_e64 s[36:37], s3, v2
	v_cmp_le_u32_e32 vcc, s3, v3
	s_bcnt1_i32_b64 s12, s[36:37]
	s_bcnt1_i32_b64 s13, vcc
	s_add_i32 s13, s13, s12
	s_cmp_gt_u32 s13, 15
	s_cselect_b32 s2, s3, s2
	s_cmp_eq_u32 s13, 16
	s_cbranch_scc1 .Ltopk_tail2
	s_or_b32 s3, s2, 0x800000
	v_cmp_le_u32_e64 s[36:37], s3, v2
	v_cmp_le_u32_e32 vcc, s3, v3
	s_bcnt1_i32_b64 s12, s[36:37]
	s_bcnt1_i32_b64 s13, vcc
	s_add_i32 s13, s13, s12
	s_cmp_gt_u32 s13, 15
	s_cselect_b32 s2, s3, s2
	s_cmp_eq_u32 s13, 16
	s_cbranch_scc1 .Ltopk_tail2
	s_or_b32 s3, s2, 0x400000
	v_cmp_le_u32_e64 s[36:37], s3, v2
	v_cmp_le_u32_e32 vcc, s3, v3
	s_bcnt1_i32_b64 s12, s[36:37]
	s_bcnt1_i32_b64 s13, vcc
	s_add_i32 s13, s13, s12
	s_cmp_gt_u32 s13, 15
	s_cselect_b32 s2, s3, s2
	s_cmp_eq_u32 s13, 16
	s_cbranch_scc1 .Ltopk_tail2
	s_or_b32 s3, s2, 0x200000
	v_cmp_le_u32_e64 s[36:37], s3, v2
	v_cmp_le_u32_e32 vcc, s3, v3
	s_bcnt1_i32_b64 s12, s[36:37]
	s_bcnt1_i32_b64 s13, vcc
	s_add_i32 s13, s13, s12
	s_cmp_gt_u32 s13, 15
	s_cselect_b32 s2, s3, s2
	s_cmp_eq_u32 s13, 16
	s_cbranch_scc1 .Ltopk_tail2
	s_or_b32 s3, s2, 0x100000
	v_cmp_le_u32_e64 s[36:37], s3, v2
	v_cmp_le_u32_e32 vcc, s3, v3
	s_bcnt1_i32_b64 s12, s[36:37]
	s_bcnt1_i32_b64 s13, vcc
	s_add_i32 s13, s13, s12
	s_cmp_gt_u32 s13, 15
	s_cselect_b32 s2, s3, s2
	s_cmp_eq_u32 s13, 16
	s_cbranch_scc1 .Ltopk_tail2
	s_or_b32 s3, s2, 0x80000
	v_cmp_le_u32_e64 s[36:37], s3, v2
	v_cmp_le_u32_e32 vcc, s3, v3
	s_bcnt1_i32_b64 s12, s[36:37]
	s_bcnt1_i32_b64 s13, vcc
	s_add_i32 s13, s13, s12
	s_cmp_gt_u32 s13, 15
	s_cselect_b32 s2, s3, s2
	s_cmp_eq_u32 s13, 16
	s_cbranch_scc1 .Ltopk_tail2
	s_or_b32 s3, s2, 0x40000
	v_cmp_le_u32_e64 s[36:37], s3, v2
	v_cmp_le_u32_e32 vcc, s3, v3
	s_bcnt1_i32_b64 s12, s[36:37]
	s_bcnt1_i32_b64 s13, vcc
	s_add_i32 s13, s13, s12
	s_cmp_gt_u32 s13, 15
	s_cselect_b32 s2, s3, s2
	s_cmp_eq_u32 s13, 16
	s_cbranch_scc1 .Ltopk_tail2
	s_or_b32 s3, s2, 0x20000
	v_cmp_le_u32_e64 s[36:37], s3, v2
	v_cmp_le_u32_e32 vcc, s3, v3
	s_bcnt1_i32_b64 s12, s[36:37]
	s_bcnt1_i32_b64 s13, vcc
	s_add_i32 s13, s13, s12
	s_cmp_gt_u32 s13, 15
	s_cselect_b32 s2, s3, s2
	s_cmp_eq_u32 s13, 16
	s_cbranch_scc1 .Ltopk_tail2
	s_or_b32 s3, s2, 0x10000
	v_cmp_le_u32_e64 s[36:37], s3, v2
	v_cmp_le_u32_e32 vcc, s3, v3
	s_bcnt1_i32_b64 s12, s[36:37]
	s_bcnt1_i32_b64 s13, vcc
	s_add_i32 s13, s13, s12
	s_cmp_gt_u32 s13, 15
	s_cselect_b32 s2, s3, s2
	s_cmp_eq_u32 s13, 16
	s_cbranch_scc1 .Ltopk_tail2
	s_or_b32 s3, s2, 0x8000
	v_cmp_le_u32_e64 s[36:37], s3, v2
	v_cmp_le_u32_e32 vcc, s3, v3
	s_bcnt1_i32_b64 s12, s[36:37]
	s_bcnt1_i32_b64 s13, vcc
	s_add_i32 s13, s13, s12
	s_cmp_gt_u32 s13, 15
	s_cselect_b32 s2, s3, s2
	s_cmp_eq_u32 s13, 16
	s_cbranch_scc1 .Ltopk_tail2
	s_or_b32 s3, s2, 0x4000
	v_cmp_le_u32_e64 s[36:37], s3, v2
	v_cmp_le_u32_e32 vcc, s3, v3
	s_bcnt1_i32_b64 s12, s[36:37]
	s_bcnt1_i32_b64 s13, vcc
	s_add_i32 s13, s13, s12
	s_cmp_gt_u32 s13, 15
	s_cselect_b32 s2, s3, s2
	s_cmp_eq_u32 s13, 16
	s_cbranch_scc1 .Ltopk_tail2
	s_or_b32 s3, s2, 0x2000
	v_cmp_le_u32_e64 s[36:37], s3, v2
	v_cmp_le_u32_e32 vcc, s3, v3
	s_bcnt1_i32_b64 s12, s[36:37]
	s_bcnt1_i32_b64 s13, vcc
	s_add_i32 s13, s13, s12
	s_cmp_gt_u32 s13, 15
	s_cselect_b32 s2, s3, s2
	s_cmp_eq_u32 s13, 16
	s_cbranch_scc1 .Ltopk_tail2
	s_or_b32 s3, s2, 0x1000
	v_cmp_le_u32_e64 s[36:37], s3, v2
	v_cmp_le_u32_e32 vcc, s3, v3
	s_bcnt1_i32_b64 s12, s[36:37]
	s_bcnt1_i32_b64 s13, vcc
	s_add_i32 s13, s13, s12
	s_cmp_gt_u32 s13, 15
	s_cselect_b32 s2, s3, s2
	s_cmp_eq_u32 s13, 16
	s_cbranch_scc1 .Ltopk_tail2
	s_or_b32 s3, s2, 0x800
	v_cmp_le_u32_e64 s[36:37], s3, v2
	v_cmp_le_u32_e32 vcc, s3, v3
	s_bcnt1_i32_b64 s12, s[36:37]
	s_bcnt1_i32_b64 s13, vcc
	s_add_i32 s13, s13, s12
	s_cmp_gt_u32 s13, 15
	s_cselect_b32 s2, s3, s2
	s_cmp_eq_u32 s13, 16
	s_cbranch_scc1 .Ltopk_tail2
	s_or_b32 s3, s2, 0x400
	v_cmp_le_u32_e64 s[36:37], s3, v2
	v_cmp_le_u32_e32 vcc, s3, v3
	s_bcnt1_i32_b64 s12, s[36:37]
	s_bcnt1_i32_b64 s13, vcc
	s_add_i32 s13, s13, s12
	s_cmp_gt_u32 s13, 15
	s_cselect_b32 s2, s3, s2
	s_cmp_eq_u32 s13, 16
	s_cbranch_scc1 .Ltopk_tail2
	s_or_b32 s3, s2, 0x200
	v_cmp_le_u32_e64 s[36:37], s3, v2
	v_cmp_le_u32_e32 vcc, s3, v3
	s_bcnt1_i32_b64 s12, s[36:37]
	s_bcnt1_i32_b64 s13, vcc
	s_add_i32 s13, s13, s12
	s_cmp_gt_u32 s13, 15
	s_cselect_b32 s2, s3, s2
	s_cmp_eq_u32 s13, 16
	s_cbranch_scc1 .Ltopk_tail2
	s_or_b32 s3, s2, 0x100
	v_cmp_le_u32_e64 s[36:37], s3, v2
	v_cmp_le_u32_e32 vcc, s3, v3
	s_bcnt1_i32_b64 s12, s[36:37]
	s_bcnt1_i32_b64 s13, vcc
	s_add_i32 s13, s13, s12
	s_cmp_gt_u32 s13, 15
	s_cselect_b32 s2, s3, s2
	s_cmp_eq_u32 s13, 16
	s_cbranch_scc1 .Ltopk_tail2
	s_or_b32 s3, s2, 0x80
	v_cmp_le_u32_e64 s[36:37], s3, v2
	v_cmp_le_u32_e32 vcc, s3, v3
	s_bcnt1_i32_b64 s12, s[36:37]
	s_bcnt1_i32_b64 s13, vcc
	s_add_i32 s13, s13, s12
	s_cmp_gt_u32 s13, 15
	s_cselect_b32 s2, s3, s2
	s_cmp_eq_u32 s13, 16
	s_cbranch_scc1 .Ltopk_tail2
	s_or_b32 s3, s2, 64
	v_cmp_le_u32_e64 s[36:37], s3, v2
	v_cmp_le_u32_e32 vcc, s3, v3
	s_bcnt1_i32_b64 s12, s[36:37]
	s_bcnt1_i32_b64 s13, vcc
	s_add_i32 s13, s13, s12
	s_cmp_gt_u32 s13, 15
	s_cselect_b32 s2, s3, s2
	s_cmp_eq_u32 s13, 16
	s_cbranch_scc1 .Ltopk_tail2
	s_or_b32 s3, s2, 32
	v_cmp_le_u32_e64 s[36:37], s3, v2
	v_cmp_le_u32_e32 vcc, s3, v3
	s_bcnt1_i32_b64 s12, s[36:37]
	s_bcnt1_i32_b64 s13, vcc
	s_add_i32 s13, s13, s12
	s_cmp_gt_u32 s13, 15
	s_cselect_b32 s2, s3, s2
	s_cmp_eq_u32 s13, 16
	s_cbranch_scc1 .Ltopk_tail2
	s_or_b32 s3, s2, 16
	v_cmp_le_u32_e64 s[36:37], s3, v2
	v_cmp_le_u32_e32 vcc, s3, v3
	s_bcnt1_i32_b64 s12, s[36:37]
	s_bcnt1_i32_b64 s13, vcc
	s_add_i32 s13, s13, s12
	s_cmp_gt_u32 s13, 15
	s_cselect_b32 s2, s3, s2
	s_cmp_eq_u32 s13, 16
	s_cbranch_scc1 .Ltopk_tail2
	s_or_b32 s3, s2, 8
	v_cmp_le_u32_e64 s[36:37], s3, v2
	v_cmp_le_u32_e32 vcc, s3, v3
	s_bcnt1_i32_b64 s12, s[36:37]
	s_bcnt1_i32_b64 s13, vcc
	s_add_i32 s13, s13, s12
	s_cmp_gt_u32 s13, 15
	s_cselect_b32 s2, s3, s2
	s_cmp_eq_u32 s13, 16
	s_cbranch_scc1 .Ltopk_tail2
	s_or_b32 s3, s2, 4
	v_cmp_le_u32_e64 s[36:37], s3, v2
	v_cmp_le_u32_e32 vcc, s3, v3
	s_bcnt1_i32_b64 s12, s[36:37]
	s_bcnt1_i32_b64 s13, vcc
	s_add_i32 s13, s13, s12
	s_cmp_gt_u32 s13, 15
	s_cselect_b32 s2, s3, s2
	s_cmp_eq_u32 s13, 16
	s_cbranch_scc1 .Ltopk_tail2
	s_or_b32 s3, s2, 2
	v_cmp_le_u32_e64 s[36:37], s3, v2
	v_cmp_le_u32_e32 vcc, s3, v3
	s_bcnt1_i32_b64 s12, s[36:37]
	s_bcnt1_i32_b64 s13, vcc
	s_add_i32 s13, s13, s12
	s_cmp_gt_u32 s13, 15
	s_cselect_b32 s2, s3, s2
	s_cmp_eq_u32 s13, 16
	s_cbranch_scc1 .Ltopk_tail2
	s_or_b32 s3, s2, 1
	v_cmp_le_u32_e64 s[36:37], s3, v2
	v_cmp_le_u32_e32 vcc, s3, v3
	s_bcnt1_i32_b64 s12, s[36:37]
	s_bcnt1_i32_b64 s13, vcc
	s_add_i32 s13, s13, s12
	s_cmp_gt_u32 s13, 15
	s_cselect_b32 s2, s3, s2
.Ltopk_tail2:
	v_cmp_eq_u32_e64 s[38:39], s2, v2
	v_cmp_lt_u32_e32 vcc, s2, v2
	v_cmp_lt_u32_e64 s[36:37], s2, v3
	v_cmp_eq_u32_e64 s[40:41], s2, v3
	v_and_b32_e32 v3, s38, v170
	s_bcnt1_i32_b64 s3, vcc
	s_bcnt1_i32_b64 s12, s[36:37]
	v_and_b32_e32 v2, s39, v163
	v_bcnt_u32_b32 v3, v3, 0
	v_and_b32_e32 v20, s40, v170
	s_add_i32 s3, s3, s12
	v_bcnt_u32_b32 v2, v2, v3
	v_and_b32_e32 v3, s41, v163
	v_bcnt_u32_b32 v20, v20, 0
	s_sub_i32 s12, 16, s3
	s_bcnt1_i32_b64 s2, s[38:39]
	v_bcnt_u32_b32 v3, v3, v20
	v_add_u32_e32 v3, s2, v3
	v_cmp_gt_i32_e64 s[42:43], s12, v2
	s_and_b64 s[2:3], s[38:39], s[42:43]
	v_cmp_gt_i32_e64 s[38:39], s12, v3
	s_and_b64 s[18:19], s[40:41], s[38:39]
	s_or_b64 s[2:3], vcc, s[2:3]
	v_cndmask_b32_e64 v2, 0, 1, s[2:3]
	s_or_b64 s[2:3], s[36:37], s[18:19]
	v_cmp_ne_u32_e64 s[12:13], 0, v2
	v_cndmask_b32_e64 v2, 0, 1, s[2:3]
	v_cmp_ne_u32_e32 vcc, 0, v2
	s_and_saveexec_b64 s[2:3], s[34:35]
	s_cbranch_execz .LBB0_233
	s_add_i32 s18, s15, 0
	s_add_i32 s18, s18, 0x22200
	v_mov_b32_e32 v20, s12
	v_mov_b32_e32 v21, s13
	v_mov_b32_e32 v22, vcc_lo
	v_mov_b32_e32 v23, vcc_hi
	v_mov_b32_e32 v2, s18
	ds_write_b128 v2, v[20:23]
	s_branch .LBB0_233
